# attention: 20 provably redundant duplicate s_waitcnt lgkmcnt(0) removed (a full LDS wait already precedes with no LDS/SMEM op in between)
# baseline (speedup 1.0000x reference)
.LBB0_348:
	ds_read_b128 v[24:27], v242 offset:16
	ds_read_b128 v[28:31], v242 offset:144
	s_bfe_u32 s88, s33, 0x40002
	s_lshl_b32 s68, s88, 7
	v_add_u32_e32 v0, s68, v186
	v_max_i32_e32 v0, 0, v0
	v_lshlrev_b32_e32 v96, 7, v0
	v_lshl_add_u64 v[48:49], v[142:143], 0, v[96:97]
	v_lshl_add_u64 v[98:99], v[144:145], 0, v[96:97]
	s_add_i32 s58, s68, 0xffffff80
	v_add_u32_e32 v230, s58, v250
	v_lshl_add_u32 v230, v230, 7, v248
	v_max_i32_e32 v231, v248, v230
	global_load_dwordx4 v[116:119], v231, s[82:83]
	global_load_dwordx4 v[154:157], v231, s[92:93]
	v_add_u32_e32 v230, 0x400, v230
	v_max_i32_e32 v231, v248, v230
	global_load_dwordx4 v[44:47], v231, s[82:83]
	global_load_dwordx4 v[68:71], v231, s[92:93]
	v_add_u32_e32 v230, 0x400, v230
	v_max_i32_e32 v231, v248, v230
	global_load_dwordx4 v[158:161], v231, s[82:83]
	global_load_dwordx4 v[162:165], v231, s[92:93]
	v_add_u32_e32 v230, 0x400, v230
	v_max_i32_e32 v231, v248, v230
	global_load_dwordx4 v[40:43], v231, s[82:83]
	global_load_dwordx4 v[48:51], v231, s[92:93]
	ds_read_b128 v[72:75], v242
	ds_read_b128 v[16:19], v242 offset:48
	ds_read_b128 v[32:35], v242 offset:32
	ds_read_b128 v[20:23], v242 offset:176
	ds_read_b128 v[36:39], v242 offset:160
	ds_read_b128 v[76:79], v242 offset:128
	s_mov_b32 s0, s97
	s_and_b32 s97, s90, 12
	s_and_b32 s89, s96, 0xfffff800
	v_readlane_b32 s55, v255, 14
	s_waitcnt vmcnt(12)
	v_and_b32_e32 v224, 63, v251
	v_lshrrev_b32_e32 v225, 3, v224
	s_movk_i32 s58, 0x90
	v_mul_u32_u24_e32 v226, 0x1200, v254
	v_add_u32_e32 v226, 0x12000, v226
	v_and_b32_e32 v227, 7, v224
	v_lshlrev_b32_e32 v227, 4, v227
	v_mad_u32_u24 v227, v225, s58, v227
	v_add_u32_e32 v227, v227, v226
	v_lshrrev_b32_e32 v225, 1, v224
	v_and_b32_e32 v224, 1, v224
	v_lshlrev_b32_e32 v224, 5, v224
	v_mad_u32_u24 v224, v225, s58, v224
	v_add_u32_e32 v224, v224, v226
	ds_write_b128 v227, v[80:83]
	ds_write_b128 v227, v[84:87] offset:1152
	ds_write_b128 v227, v[88:91] offset:2304
	ds_write_b128 v227, v[92:95] offset:3456
	ds_read_b128 v[80:83], v224
	ds_read_b128 v[84:87], v224 offset:16
	ds_read_b128 v[92:95], v224 offset:64
	ds_read_b128 v[88:91], v224 offset:80
	s_waitcnt lgkmcnt(0)
	v_and_b32_e32 v64, 0xffff0000, v84
	v_lshlrev_b32_e32 v65, 16, v84
	v_and_b32_e32 v60, 0xffff0000, v85
	v_lshlrev_b32_e32 v61, 16, v85
	s_add_i32 s97, s97, s55
	v_or_b32_e32 v8, s89, v185
	v_and_b32_e32 v66, 0xffff0000, v88
	v_lshlrev_b32_e32 v67, 16, v88
	v_and_b32_e32 v62, 0xffff0000, v89
	v_lshlrev_b32_e32 v63, 16, v89
	v_pk_mul_f32 v[0:1], v[64:65], v[64:65]
	v_pk_mul_f32 v[2:3], v[60:61], v[60:61]
	v_or_b32_e32 v8, s68, v8
	s_lshl_b32 s94, s97, 7
	v_and_b32_e32 v56, 0xffff0000, v86
	v_lshlrev_b32_e32 v57, 16, v86
	v_and_b32_e32 v52, 0xffff0000, v87
	v_lshlrev_b32_e32 v53, 16, v87
	v_pk_fma_f32 v[214:215], v[66:67], v[66:67], v[0:1]
	v_pk_fma_f32 v[216:217], v[62:63], v[62:63], v[2:3]
	v_or_b32_e32 v2, 32, v8
	v_and_b32_e32 v58, 0xffff0000, v90
	v_lshlrev_b32_e32 v59, 16, v90
	v_and_b32_e32 v54, 0xffff0000, v91
	v_lshlrev_b32_e32 v55, 16, v91
	v_pk_mul_f32 v[4:5], v[56:57], v[56:57]
	v_pk_mul_f32 v[6:7], v[52:53], v[52:53]
	v_pk_fma_f32 v[218:219], v[58:59], v[58:59], v[4:5]
	v_pk_fma_f32 v[220:221], v[54:55], v[54:55], v[6:7]
	v_readlane_b32 s78, v255, 6
	v_readlane_b32 s79, v255, 7
	s_or_b32 s58, s89, s68
	s_or_b32 s58, s58, s91
	v_and_b32_e32 v231, 7, v250
	v_add_u32_e32 v231, s58, v231
	v_add_u32_e32 v230, s94, v248
	v_mad_u32_u24 v230, v231, s65, v230
	s_nop 0
	global_load_dwordx4 v[0:3], v230, s[78:79]
	v_add_u32_e32 v230, 0x6000, v230
	global_load_dwordx4 v[4:7], v230, s[78:79]
	v_add_u32_e32 v230, 0x6000, v230
	global_load_dwordx4 v[8:11], v230, s[78:79]
	v_add_u32_e32 v230, 0x6000, v230
	global_load_dwordx4 v[12:15], v230, s[78:79]
	v_add_u32_e32 v230, 0x6000, v230
	global_load_dwordx4 v[100:103], v230, s[78:79]
	v_add_u32_e32 v230, 0x6000, v230
	global_load_dwordx4 v[104:107], v230, s[78:79]
	v_add_u32_e32 v230, 0x6000, v230
	global_load_dwordx4 v[108:111], v230, s[78:79]
	v_add_u32_e32 v230, 0x6000, v230
	global_load_dwordx4 v[112:115], v230, s[78:79]
	v_lshlrev_b32_e32 v239, 16, v92
	v_lshlrev_b32_e32 v238, 16, v80
	v_and_b32_e32 v245, 0xffff0000, v92
	v_and_b32_e32 v244, 0xffff0000, v80
	v_lshlrev_b32_e32 v229, 16, v93
	v_lshlrev_b32_e32 v228, 16, v81
	v_pk_mul_f32 v[240:241], v[238:239], v[238:239]
	v_pk_mul_f32 v[246:247], v[244:245], v[244:245]
	v_pk_mul_f32 v[230:231], v[228:229], v[228:229]
	v_and_b32_e32 v235, 0xffff0000, v93
	v_and_b32_e32 v234, 0xffff0000, v81
	v_lshlrev_b32_e32 v171, 16, v94
	v_lshlrev_b32_e32 v170, 16, v82
	v_pk_mul_f32 v[236:237], v[234:235], v[234:235]
	v_and_b32_e32 v173, 0xffff0000, v94
	v_and_b32_e32 v172, 0xffff0000, v82
	v_pk_mul_f32 v[178:179], v[170:171], v[170:171]
	v_lshlrev_b32_e32 v167, 16, v95
	v_lshlrev_b32_e32 v166, 16, v83
	v_pk_mul_f32 v[180:181], v[172:173], v[172:173]
	v_and_b32_e32 v169, 0xffff0000, v95
	v_and_b32_e32 v168, 0xffff0000, v83
	v_pk_mul_f32 v[174:175], v[166:167], v[166:167]
	v_pk_mul_f32 v[176:177], v[168:169], v[168:169]
	v_readlane_b32 s76, v255, 1
	s_add_i32 s33, s33, s76
	v_readlane_b32 s77, v255, 2
	s_cmpk_gt_i32 s33, 0x3ff
	s_cselect_b64 s[76:77], -1, 0
	v_mov_b32_e32 v98, v26
	v_mov_b32_e32 v223, v28
	v_add_f32_e32 v26, v247, v246
	v_add_f32_e32 v28, v241, v240
	v_add_f32_e32 v26, v28, v26
	v_add_f32_e32 v28, v231, v230
	v_mov_b32_e32 v222, v24
	v_add_f32_e32 v24, v237, v236
	v_add_f32_e32 v26, v28, v26
	v_add_f32_e32 v24, v24, v26
	v_add_f32_e32 v26, v179, v178
	v_add_f32_e32 v24, v26, v24
	v_add_f32_e32 v26, v181, v180
	v_add_f32_e32 v24, v26, v24
	v_add_f32_e32 v26, v175, v174
	v_add_f32_e32 v24, v26, v24
	v_add_f32_e32 v26, v177, v176
	v_add_f32_e32 v24, v26, v24
	v_add_f32_e32 v24, v215, v24
	v_add_f32_e32 v24, v214, v24
	v_add_f32_e32 v24, v217, v24
	v_add_f32_e32 v24, v216, v24
	v_add_f32_e32 v24, v219, v24
	v_add_f32_e32 v24, v218, v24
	v_add_f32_e32 v24, v221, v24
	v_add_f32_e32 v24, v220, v24
	s_waitcnt vmcnt(8)
	ds_write_b128 v227, v[116:119]
	ds_write_b128 v227, v[44:47] offset:1152
	ds_write_b128 v227, v[158:161] offset:2304
	ds_write_b128 v227, v[40:43] offset:3456
	v_and_b32_e32 v225, 63, v251
	v_lshrrev_b32_e32 v224, 1, v225
	v_and_b32_e32 v225, 1, v225
	v_lshlrev_b32_e32 v225, 6, v225
	v_mul_u32_u24_e32 v224, 0x90, v224
	v_add3_u32 v225, v224, v225, v226
	ds_read_b128 v[116:119], v225
	ds_read_b128 v[44:47], v225 offset:16
	ds_read_b128 v[158:161], v225 offset:32
	ds_read_b128 v[40:43], v225 offset:48
	ds_write_b128 v227, v[154:157]
	ds_write_b128 v227, v[68:71] offset:1152
	ds_write_b128 v227, v[162:165] offset:2304
	ds_write_b128 v227, v[48:51] offset:3456
	ds_read_b128 v[154:157], v225
	ds_read_b128 v[68:71], v225 offset:16
	ds_read_b128 v[162:165], v225 offset:32
	ds_read_b128 v[48:51], v225 offset:48
	s_waitcnt lgkmcnt(0)
	v_mov_b32_e32 v176, v72
	v_mov_b32_e32 v177, v76
	v_mov_b32_e32 v178, v116
	v_mov_b32_e32 v179, v154
	s_nop 1
	v_add_f32_dpp v24, v24, v24 quad_perm:[1,0,3,2] row_mask:0xf bank_mask:0xf
	v_fmamk_f32 v24, v24, 0x3c800000, v189
	v_rsq_f32_e32 v24, v24
	v_mov_b32_e32 v76, v73
	v_mov_b32_e32 v232, v74
	v_mov_b32_e32 v233, v78
	v_pk_mul_f32 v[180:181], v[24:25], v[238:239] op_sel_hi:[0,1]
	v_pk_mul_f32 v[176:177], v[176:177], v[180:181]
	v_mov_b32_e32 v174, v118
	v_pk_mul_f32 v[178:179], v[178:179], v[176:177]
	v_mov_b32_e32 v175, v156
	v_sub_f32_e32 v96, v178, v179
	v_mov_b32_e32 v178, v154
	v_mov_b32_e32 v179, v116
	v_pk_mul_f32 v[176:177], v[178:179], v[176:177]
	v_mov_b32_e32 v154, v117
	v_add_f32_e32 v153, v177, v176
	v_pk_mul_f32 v[176:177], v[24:25], v[244:245] op_sel_hi:[0,1]
	v_pk_mul_f32 v[72:73], v[76:77], v[176:177]
	v_mov_b32_e32 v116, v155
	v_pk_mul_f32 v[76:77], v[154:155], v[72:73]
	v_pk_mul_f32 v[72:73], v[116:117], v[72:73]
	v_sub_f32_e32 v154, v76, v77
	v_add_f32_e32 v116, v73, v72
	v_pk_mul_f32 v[72:73], v[24:25], v[228:229] op_sel_hi:[0,1]
	v_pk_mul_f32 v[72:73], v[232:233], v[72:73]
	v_mov_b32_e32 v78, v75
	v_pk_mul_f32 v[76:77], v[174:175], v[72:73]
	v_mov_b32_e32 v226, v44
	v_sub_f32_e32 v117, v76, v77
	v_mov_b32_e32 v76, v156
	v_mov_b32_e32 v77, v118
	v_pk_mul_f32 v[72:73], v[76:77], v[72:73]
	v_mov_b32_e32 v156, v119
	v_add_f32_e32 v76, v73, v72
	v_pk_mul_f32 v[72:73], v[24:25], v[234:235] op_sel_hi:[0,1]
	v_pk_mul_f32 v[72:73], v[78:79], v[72:73]
	v_mov_b32_e32 v118, v157
	v_pk_mul_f32 v[74:75], v[156:157], v[72:73]
	v_pk_mul_f32 v[72:73], v[118:119], v[72:73]
	v_mov_b32_e32 v227, v68
	v_add_f32_e32 v78, v73, v72
	v_pk_mul_f32 v[72:73], v[24:25], v[170:171] op_sel_hi:[0,1]
	v_pk_mul_f32 v[72:73], v[72:73], v[222:223]
	v_sub_f32_e32 v77, v74, v75
	v_pk_mul_f32 v[74:75], v[72:73], v[226:227]
	v_mov_b32_e32 v28, v25
	v_sub_f32_e32 v79, v74, v75
	v_mov_b32_e32 v74, v68
	v_mov_b32_e32 v75, v44
	v_pk_mul_f32 v[72:73], v[72:73], v[74:75]
	v_mov_b32_e32 v68, v45
	v_add_f32_e32 v74, v73, v72
	v_pk_mul_f32 v[72:73], v[24:25], v[172:173] op_sel_hi:[0,1]
	v_pk_mul_f32 v[28:29], v[72:73], v[28:29]
	v_mov_b32_e32 v44, v69
	v_pk_mul_f32 v[72:73], v[28:29], v[68:69]
	v_pk_mul_f32 v[28:29], v[28:29], v[44:45]
	v_sub_f32_e32 v25, v72, v73
	v_mov_b32_e32 v99, v30
	v_add_f32_e32 v68, v29, v28
	v_pk_mul_f32 v[28:29], v[24:25], v[166:167] op_sel_hi:[0,1]
	v_mov_b32_e32 v224, v46
	v_mov_b32_e32 v225, v70
	v_pk_mul_f32 v[28:29], v[28:29], v[98:99]
	v_mov_b32_e32 v30, v27
	v_pk_mul_f32 v[44:45], v[28:29], v[224:225]
	s_and_b64 vcc, exec, s[76:77]
	v_sub_f32_e32 v69, v44, v45
	v_mov_b32_e32 v44, v70
	v_mov_b32_e32 v45, v46
	v_pk_mul_f32 v[28:29], v[28:29], v[44:45]
	v_mov_b32_e32 v70, v47
	v_add_f32_e32 v44, v29, v28
	v_pk_mul_f32 v[28:29], v[24:25], v[168:169] op_sel_hi:[0,1]
	v_pk_mul_f32 v[26:27], v[28:29], v[30:31]
	v_mov_b32_e32 v46, v71
	v_pk_mul_f32 v[28:29], v[26:27], v[70:71]
	v_pk_mul_f32 v[26:27], v[26:27], v[46:47]
	v_sub_f32_e32 v30, v28, v29
	v_add_f32_e32 v31, v27, v26
	v_mov_b32_e32 v26, v65
	v_mov_b32_e32 v27, v67
	v_pk_mul_f32 v[26:27], v[24:25], v[26:27] op_sel_hi:[0,1]
	v_mov_b32_e32 v28, v32
	v_mov_b32_e32 v29, v36
	v_pk_mul_f32 v[26:27], v[26:27], v[28:29]
	v_mov_b32_e32 v28, v158
	v_mov_b32_e32 v29, v162
	v_pk_mul_f32 v[28:29], v[26:27], v[28:29]
	v_mov_b32_e32 v65, v66
	v_sub_f32_e32 v32, v28, v29
	v_mov_b32_e32 v28, v162
	v_mov_b32_e32 v29, v158
	v_pk_mul_f32 v[26:27], v[26:27], v[28:29]
	v_mov_b32_e32 v36, v33
	v_add_f32_e32 v45, v27, v26
	v_pk_mul_f32 v[26:27], v[24:25], v[64:65] op_sel_hi:[0,1]
	v_pk_mul_f32 v[26:27], v[26:27], v[36:37]
	v_mov_b32_e32 v162, v159
	v_mov_b32_e32 v158, v163
	v_pk_mul_f32 v[28:29], v[26:27], v[162:163]
	v_pk_mul_f32 v[26:27], v[26:27], v[158:159]
	v_sub_f32_e32 v33, v28, v29
	v_add_f32_e32 v36, v27, v26
	v_mov_b32_e32 v26, v61
	v_mov_b32_e32 v27, v63
	v_pk_mul_f32 v[26:27], v[24:25], v[26:27] op_sel_hi:[0,1]
	v_mov_b32_e32 v28, v34
	v_mov_b32_e32 v29, v38
	v_pk_mul_f32 v[26:27], v[26:27], v[28:29]
	v_mov_b32_e32 v28, v160
	v_mov_b32_e32 v29, v164
	v_pk_mul_f32 v[28:29], v[26:27], v[28:29]
	v_mov_b32_e32 v61, v62
	v_sub_f32_e32 v34, v28, v29
	v_mov_b32_e32 v28, v164
	v_mov_b32_e32 v29, v160
	v_pk_mul_f32 v[26:27], v[26:27], v[28:29]
	v_mov_b32_e32 v38, v35
	v_add_f32_e32 v37, v27, v26
	v_pk_mul_f32 v[26:27], v[24:25], v[60:61] op_sel_hi:[0,1]
	v_pk_mul_f32 v[26:27], v[26:27], v[38:39]
	v_mov_b32_e32 v164, v161
	v_mov_b32_e32 v160, v165
	v_pk_mul_f32 v[28:29], v[26:27], v[164:165]
	v_pk_mul_f32 v[26:27], v[26:27], v[160:161]
	v_sub_f32_e32 v35, v28, v29
	v_add_f32_e32 v38, v27, v26
	v_mov_b32_e32 v26, v57
	v_mov_b32_e32 v27, v59
	v_pk_mul_f32 v[26:27], v[24:25], v[26:27] op_sel_hi:[0,1]
	v_mov_b32_e32 v28, v16
	v_mov_b32_e32 v29, v20
	v_pk_mul_f32 v[26:27], v[26:27], v[28:29]
	v_mov_b32_e32 v28, v40
	v_mov_b32_e32 v29, v48
	v_pk_mul_f32 v[28:29], v[26:27], v[28:29]
	v_mov_b32_e32 v57, v58
	v_sub_f32_e32 v39, v28, v29
	v_mov_b32_e32 v28, v48
	v_mov_b32_e32 v29, v40
	v_pk_mul_f32 v[26:27], v[26:27], v[28:29]
	v_mov_b32_e32 v20, v17
	v_add_f32_e32 v28, v27, v26
	v_pk_mul_f32 v[26:27], v[24:25], v[56:57] op_sel_hi:[0,1]
	v_pk_mul_f32 v[16:17], v[26:27], v[20:21]
	v_mov_b32_e32 v48, v41
	v_mov_b32_e32 v40, v49
	v_pk_mul_f32 v[20:21], v[16:17], v[48:49]
	v_pk_mul_f32 v[16:17], v[16:17], v[40:41]
	v_sub_f32_e32 v26, v20, v21
	v_add_f32_e32 v27, v17, v16
	v_mov_b32_e32 v16, v53
	v_mov_b32_e32 v17, v55
	v_pk_mul_f32 v[16:17], v[24:25], v[16:17] op_sel_hi:[0,1]
	v_mov_b32_e32 v20, v18
	v_mov_b32_e32 v21, v22
	v_pk_mul_f32 v[16:17], v[16:17], v[20:21]
	v_mov_b32_e32 v20, v42
	v_mov_b32_e32 v21, v50
	v_pk_mul_f32 v[20:21], v[16:17], v[20:21]
	v_mov_b32_e32 v53, v54
	v_sub_f32_e32 v29, v20, v21
	v_mov_b32_e32 v20, v50
	v_mov_b32_e32 v21, v42
	v_pk_mul_f32 v[16:17], v[16:17], v[20:21]
	v_mov_b32_e32 v22, v19
	v_add_f32_e32 v20, v17, v16
	v_pk_mul_f32 v[16:17], v[24:25], v[52:53] op_sel_hi:[0,1]
	v_pk_mul_f32 v[16:17], v[16:17], v[22:23]
	v_mov_b32_e32 v50, v43
	v_mov_b32_e32 v42, v51
	v_pk_mul_f32 v[18:19], v[16:17], v[50:51]
	v_pk_mul_f32 v[16:17], v[16:17], v[42:43]
	v_sub_f32_e32 v21, v18, v19
	v_add_f32_e32 v22, v17, v16
	v_cvt_pk_bf16_f32 v16, v96, v154
	v_cvt_pk_bf16_f32 v17, v117, v77
	v_cvt_pk_bf16_f32 v18, v79, v25
	v_cvt_pk_bf16_f32 v19, v69, v30
	s_barrier
	ds_write_b128 v190, v[16:19]
	v_cvt_pk_bf16_f32 v16, v32, v33
	v_cvt_pk_bf16_f32 v17, v34, v35
	v_cvt_pk_bf16_f32 v18, v39, v26
	v_cvt_pk_bf16_f32 v19, v29, v21
	ds_write_b128 v190, v[16:19] offset:16
	v_cvt_pk_bf16_f32 v16, v153, v116
	v_cvt_pk_bf16_f32 v17, v76, v78
	v_cvt_pk_bf16_f32 v18, v74, v68
	v_cvt_pk_bf16_f32 v19, v44, v31
	ds_write_b128 v190, v[16:19] offset:64
	v_cvt_pk_bf16_f32 v16, v45, v36
	v_cvt_pk_bf16_f32 v17, v37, v38
	v_cvt_pk_bf16_f32 v18, v28, v27
	v_cvt_pk_bf16_f32 v19, v20, v22
	ds_write_b128 v190, v[16:19] offset:80
	v_and_b32_e32 v20, 63, v251
	v_lshrrev_b32_e32 v21, 3, v20
	v_mul_u32_u24_e32 v21, 0x90, v21
	v_and_b32_e32 v22, 7, v20
	v_lshl_add_u32 v21, v22, 4, v21
	v_mul_u32_u24_e32 v22, 0x1200, v254
	v_add_u32_e32 v22, 0x12000, v22
	v_add_u32_e32 v21, v21, v22
	v_lshrrev_b32_e32 v23, 2, v20
	v_mul_u32_u24_e32 v23, 0x120, v23
	v_and_b32_e32 v20, 3, v20
	v_lshl_add_u32 v23, v20, 3, v23
	v_add_u32_e32 v23, v23, v22
	ds_write_b128 v21, v[122:125]
	ds_write_b128 v21, v[128:131] offset:1152
	ds_write_b128 v21, v[132:135] offset:2304
	ds_write_b128 v21, v[136:139] offset:3456
	ds_read_b64 v[122:123], v23
	ds_read_b64 v[124:125], v23 offset:32
	ds_read_b64 v[128:129], v23 offset:64
	ds_read_b64 v[130:131], v23 offset:96
	ds_read_b64 v[132:133], v23 offset:144
	ds_read_b64 v[136:137], v23 offset:176
	ds_read_b64 v[138:139], v23 offset:208
	ds_read_b64 v[140:141], v23 offset:240
	s_waitcnt lgkmcnt(0)
	v_and_b32_e32 v16, 0xffff, v122
	v_lshrrev_b32_e32 v17, 16, v122
	v_lshl_or_b32 v16, v132, 16, v16
	v_and_or_b32 v17, v132, s54, v17
	v_add_u32_e32 v18, 0x9000, v191
	ds_write2_b32 v18, v16, v17 offset1:130
	v_and_b32_e32 v16, 0xffff, v123
	v_lshrrev_b32_e32 v17, 16, v123
	v_lshl_or_b32 v16, v133, 16, v16
	v_and_or_b32 v17, v133, s54, v17
	v_add_u32_e32 v18, 0x9400, v191
	ds_write2_b32 v18, v16, v17 offset0:4 offset1:134
	v_and_b32_e32 v16, 0xffff, v124
	v_lshrrev_b32_e32 v17, 16, v124
	v_lshl_or_b32 v16, v136, 16, v16
	v_and_or_b32 v17, v136, s54, v17
	v_add_u32_e32 v18, 0xb000, v191
	ds_write2_b32 v18, v16, v17 offset0:32 offset1:162
	v_and_b32_e32 v16, 0xffff, v125
	v_lshrrev_b32_e32 v17, 16, v125
	v_lshl_or_b32 v16, v137, 16, v16
	v_and_or_b32 v17, v137, s54, v17
	v_add_u32_e32 v18, 0xb400, v191
	ds_write2_b32 v18, v16, v17 offset0:36 offset1:166
	v_and_b32_e32 v16, 0xffff, v128
	v_lshrrev_b32_e32 v17, 16, v128
	v_lshl_or_b32 v16, v138, 16, v16
	v_and_or_b32 v17, v138, s54, v17
	v_add_u32_e32 v18, 0xd000, v191
	ds_write2_b32 v18, v16, v17 offset0:64 offset1:194
	v_and_b32_e32 v16, 0xffff, v129
	v_lshrrev_b32_e32 v17, 16, v129
	v_lshl_or_b32 v16, v139, 16, v16
	v_and_or_b32 v17, v139, s54, v17
	v_add_u32_e32 v18, 0xd400, v191
	ds_write2_b32 v18, v16, v17 offset0:68 offset1:198
	v_and_b32_e32 v16, 0xffff, v130
	v_lshrrev_b32_e32 v17, 16, v130
	v_lshl_or_b32 v16, v140, 16, v16
	v_and_or_b32 v17, v140, s54, v17
	v_add_u32_e32 v18, 0xf000, v191
	ds_write2_b32 v18, v16, v17 offset0:96 offset1:226
	v_and_b32_e32 v16, 0xffff, v131
	v_lshrrev_b32_e32 v17, 16, v131
	v_lshl_or_b32 v16, v141, 16, v16
	v_and_or_b32 v17, v141, s54, v17
	v_add_u32_e32 v18, 0xf400, v191
	ds_write2_b32 v18, v16, v17 offset0:100 offset1:230
	s_waitcnt vmcnt(0)
	v_and_b32_e32 v16, 63, v251
	v_lshrrev_b32_e32 v17, 3, v16
	v_mul_u32_u24_e32 v17, 0x90, v17
	v_and_b32_e32 v18, 7, v16
	v_lshl_add_u32 v17, v18, 4, v17
	v_mul_u32_u24_e32 v18, 0x1200, v254
	v_add_u32_e32 v18, 0x12000, v18
	v_add_u32_e32 v17, v17, v18
	v_and_b32_e32 v19, 31, v16
	v_mul_u32_u24_e32 v19, 0x90, v19
	v_lshrrev_b32_e32 v16, 5, v16
	v_lshl_add_u32 v19, v16, 4, v19
	v_add_u32_e32 v19, v19, v18
	ds_write_b128 v17, v[0:3]
	ds_write_b128 v17, v[4:7] offset:1152
	ds_write_b128 v17, v[8:11] offset:2304
	ds_write_b128 v17, v[12:15] offset:3456
	ds_read_b128 v[0:3], v19
	ds_read_b128 v[8:11], v19 offset:32
	ds_read_b128 v[4:7], v19 offset:64
	ds_read_b128 v[12:15], v19 offset:96
	ds_write_b128 v17, v[100:103]
	ds_write_b128 v17, v[104:107] offset:1152
	ds_write_b128 v17, v[108:111] offset:2304
	ds_write_b128 v17, v[112:115] offset:3456
	ds_read_b128 v[100:103], v19
	ds_read_b128 v[108:111], v19 offset:32
	ds_read_b128 v[104:107], v19 offset:64
	ds_read_b128 v[112:115], v19 offset:96
	s_waitcnt lgkmcnt(0)
	s_cbranch_vccnz .LBB0_354
	s_add_i32 s64, s1, s96
	s_and_b32 s64, s64, 0x780
	s_addk_i32 s64, 0xff80
	v_mov_b32_e32 v96, v97
	v_add_u32_e32 v16, s64, v182
	v_mov_b32_e32 v98, v97
	v_mov_b32_e32 v99, v97
	v_mov_b64_e32 v[80:81], v[96:97]
	v_mov_b64_e32 v[84:85], v[96:97]
	v_mov_b64_e32 v[92:93], v[96:97]
	v_mov_b64_e32 v[88:89], v[96:97]
	s_ashr_i32 s55, s33, 6
	s_and_b32 s69, s33, 3
	v_cmp_lt_i32_e32 vcc, -1, v16
	v_mov_b64_e32 v[82:83], v[98:99]
	v_mov_b64_e32 v[86:87], v[98:99]
	v_mov_b64_e32 v[94:95], v[98:99]
	v_mov_b64_e32 v[90:91], v[98:99]
	s_and_saveexec_b64 s[78:79], vcc
	s_cbranch_execz .LBB0_351
	v_readlane_b32 vcc_lo, v255, 6
	v_readlane_b32 vcc_hi, v255, 7
	v_add_u32_e32 v18, s64, v250
	v_lshl_add_u32 v18, s55, 11, v18
	s_lshl_b32 s94, s69, 7
	v_mov_b64_e32 v[16:17], vcc
	v_mad_i64_i32 v[16:17], vcc, v18, s65, v[16:17]
	v_lshl_add_u64 v[16:17], v[16:17], 0, s[94:95]
	v_mov_b32_e32 v153, v97
	v_lshl_add_u64 v[16:17], v[16:17], 0, v[248:249]
	s_movk_i32 s94, 0x6000
	global_load_dwordx4 v[80:83], v[16:17], off offset:2048
	v_lshl_add_u64 v[16:17], v[16:17], 0, s[94:95]
	global_load_dwordx4 v[84:87], v[16:17], off offset:2048
	v_lshl_add_u64 v[16:17], v[16:17], 0, s[94:95]
	global_load_dwordx4 v[88:91], v[16:17], off offset:2048
	v_lshl_add_u64 v[16:17], v[16:17], 0, s[94:95]
	global_load_dwordx4 v[92:95], v[16:17], off offset:2048

.Lattn_prio_skip:
	ds_read_b128 v[20:23], v243 offset:144
	ds_read_b128 v[16:19], v243 offset:16
	v_or_b32_e32 v153, s68, v184
	v_or_b32_e32 v98, s91, v153
	v_lshlrev_b32_e32 v96, 5, v98
	v_or_b32_e32 v24, v96, v126
	v_lshlrev_b32_e32 v54, 2, v24
	ds_read_b128 v[42:45], v243 offset:128
	ds_read_b128 v[24:27], v252 offset:4096
	ds_read_b128 v[28:31], v252 offset:22144
	ds_read_b128 v[46:49], v243
	ds_read_b128 v[50:53], v252
	s_nop 0
	ds_read_b128 v[54:57], v252 offset:16384
	s_lshl_b32 s55, s97, 2
	v_lshlrev_b32_e32 v34, 16, v15
	v_and_b32_e32 v32, 0xffff0000, v15
	v_lshlrev_b32_e32 v39, 16, v9
	v_and_b32_e32 v15, 0xffff0000, v9
	v_lshlrev_b32_e32 v41, 16, v8
	v_lshlrev_b32_e32 v40, 16, v12
	v_and_b32_e32 v9, 0xffff0000, v8
	v_and_b32_e32 v8, 0xffff0000, v12
	v_lshlrev_b32_e32 v12, 16, v7
	v_and_b32_e32 v58, 0xffff0000, v7
	v_lshlrev_b32_e32 v7, 16, v1
	v_and_b32_e32 v63, 0xffff0000, v1
	v_lshlrev_b32_e32 v65, 16, v0
	v_lshlrev_b32_e32 v64, 16, v4
	v_and_b32_e32 v1, 0xffff0000, v0
	v_and_b32_e32 v0, 0xffff0000, v4
	v_lshlrev_b32_e32 v35, 16, v11
	v_and_b32_e32 v33, 0xffff0000, v11
	v_lshlrev_b32_e32 v36, 16, v14
	v_lshlrev_b32_e32 v37, 16, v10
	v_and_b32_e32 v11, 0xffff0000, v10
	v_and_b32_e32 v10, 0xffff0000, v14
	v_lshlrev_b32_e32 v38, 16, v13
	v_and_b32_e32 v14, 0xffff0000, v13
	v_lshlrev_b32_e32 v13, 16, v3
	v_and_b32_e32 v59, 0xffff0000, v3
	v_lshlrev_b32_e32 v61, 16, v2
	v_lshlrev_b32_e32 v60, 16, v6
	v_and_b32_e32 v3, 0xffff0000, v2
	v_and_b32_e32 v2, 0xffff0000, v6
	v_lshlrev_b32_e32 v6, 16, v5
	v_mov_b32_e32 v99, s55
	v_pk_mul_f32 v[156:157], v[64:65], v[64:65]
	v_pk_mul_f32 v[158:159], v[0:1], v[0:1]
	v_and_b32_e32 v62, 0xffff0000, v5
	v_pk_mul_f32 v[118:119], v[6:7], v[6:7]
	v_mov_b32_e32 v214, v253
	v_add_f32_e32 v99, v157, v159
	v_pk_mul_f32 v[154:155], v[62:63], v[62:63]
	v_add_f32_e32 v99, v119, v99
	v_pk_mul_f32 v[78:79], v[60:61], v[60:61]
	v_add_f32_e32 v99, v155, v99
	v_pk_mul_f32 v[116:117], v[2:3], v[2:3]
	v_add_f32_e32 v79, v79, v99
	v_pk_mul_f32 v[74:75], v[12:13], v[12:13]
	v_add_f32_e32 v79, v117, v79
	v_pk_mul_f32 v[76:77], v[58:59], v[58:59]
	v_add_f32_e32 v75, v75, v79
	v_pk_mul_f32 v[70:71], v[40:41], v[40:41]
	v_add_f32_e32 v75, v77, v75
	v_pk_mul_f32 v[72:73], v[8:9], v[8:9]
	v_add_f32_e32 v71, v71, v75
	v_add_f32_e32 v71, v73, v71
	v_fmac_f32_e32 v71, v39, v39
	v_fmac_f32_e32 v71, v15, v15
	v_fmac_f32_e32 v71, v37, v37
	v_fmac_f32_e32 v71, v11, v11
	v_fmac_f32_e32 v71, v35, v35
	v_fmac_f32_e32 v71, v33, v33
	v_mov_b32_e32 v68, v14
	v_mov_b32_e32 v69, v38
	v_pk_mul_f32 v[68:69], v[68:69], v[68:69]
	v_mov_b32_e32 v66, v10
	v_mov_b32_e32 v67, v36
	v_pk_mul_f32 v[66:67], v[66:67], v[66:67]
	v_mov_b32_e32 v4, v32
	v_mov_b32_e32 v5, v34
	v_pk_mul_f32 v[4:5], v[4:5], v[4:5]
	s_waitcnt lgkmcnt(0)
	v_mov_b32_e32 v162, v20
	v_mov_b32_e32 v163, v16
	v_add_f32_e32 v16, v156, v71
	v_add_f32_e32 v16, v158, v16
	v_add_f32_e32 v16, v118, v16
	v_add_f32_e32 v16, v154, v16
	v_add_f32_e32 v16, v78, v16
	v_add_f32_e32 v16, v116, v16
	v_add_f32_e32 v16, v74, v16
	v_add_f32_e32 v16, v76, v16
	v_add_f32_e32 v16, v70, v16
	v_add_f32_e32 v16, v72, v16
	v_add_f32_e32 v16, v69, v16
	v_add_f32_e32 v16, v68, v16
	v_add_f32_e32 v16, v67, v16
	v_add_f32_e32 v16, v66, v16
	v_add_f32_e32 v5, v5, v16
	v_add_f32_e32 v16, v4, v5
	v_mov_b32_e32 v161, v18
	v_mov_b32_e32 v142, v16
	v_mov_b32_e32 v143, v16
	s_nop 1
	v_permlane32_swap_b32_e32 v142, v143
	v_mov_b32_e32 v66, v42
	v_mov_b32_e32 v67, v46
	v_mov_b32_e32 v46, v43
	v_mov_b32_e32 v68, v50
	v_add_f32_e32 v16, v142, v143
	v_fmamk_f32 v16, v16, 0x3c800000, v189
	v_rsq_f32_e32 v16, v16
	v_mov_b32_e32 v69, v54
	v_mov_b32_e32 v164, v44
	v_mov_b32_e32 v165, v48
	v_mul_f32_e32 v70, 0x3e38aa3b, v16
	v_pk_mul_f32 v[64:65], v[70:71], v[64:65] op_sel_hi:[0,1]
	v_pk_mul_f32 v[0:1], v[70:71], v[0:1] op_sel_hi:[0,1]
	v_pk_mul_f32 v[64:65], v[66:67], v[64:65]
	v_mov_b32_e32 v66, v54
	v_mov_b32_e32 v67, v50
	v_pk_mul_f32 v[0:1], v[46:47], v[0:1]
	v_mov_b32_e32 v50, v55
	v_mov_b32_e32 v54, v51
	v_pk_mul_f32 v[42:43], v[50:51], v[0:1]
	v_pk_mul_f32 v[0:1], v[54:55], v[0:1]
	v_sub_f32_e32 v42, v43, v42
	v_add_f32_e32 v43, v0, v1
	v_pk_mul_f32 v[0:1], v[70:71], v[6:7] op_sel_hi:[0,1]
	v_mov_b32_e32 v4, v52
	v_mov_b32_e32 v5, v56
	v_pk_mul_f32 v[0:1], v[0:1], v[164:165]
	v_mov_b32_e32 v6, v56
	v_mov_b32_e32 v7, v52
	v_pk_mul_f32 v[6:7], v[0:1], v[6:7]
	v_pk_mul_f32 v[0:1], v[0:1], v[4:5]
	v_sub_f32_e32 v6, v7, v6
	v_add_f32_e32 v7, v0, v1
	v_pk_mul_f32 v[0:1], v[70:71], v[62:63] op_sel_hi:[0,1]
	v_mov_b32_e32 v48, v45
	v_pk_mul_f32 v[0:1], v[0:1], v[48:49]
	v_mov_b32_e32 v52, v57
	v_mov_b32_e32 v56, v53
	v_pk_mul_f32 v[4:5], v[0:1], v[52:53]
	v_pk_mul_f32 v[0:1], v[0:1], v[56:57]
	v_mov_b32_e32 v168, v24
	v_add_f32_e32 v45, v0, v1
	v_pk_mul_f32 v[0:1], v[70:71], v[60:61] op_sel_hi:[0,1]
	v_mov_b32_e32 v169, v28
	v_sub_f32_e32 v44, v5, v4
	v_pk_mul_f32 v[0:1], v[0:1], v[162:163]
	v_mov_b32_e32 v4, v28
	v_mov_b32_e32 v5, v24
	v_pk_mul_f32 v[4:5], v[0:1], v[4:5]
	v_pk_mul_f32 v[0:1], v[0:1], v[168:169]
	v_sub_f32_e32 v4, v5, v4
	v_add_f32_e32 v5, v0, v1
	v_pk_mul_f32 v[0:1], v[70:71], v[2:3] op_sel_hi:[0,1]
	v_mov_b32_e32 v16, v21
	v_pk_mul_f32 v[0:1], v[0:1], v[16:17]
	v_mov_b32_e32 v24, v29
	v_mov_b32_e32 v28, v25
	v_pk_mul_f32 v[2:3], v[0:1], v[24:25]
	v_pk_mul_f32 v[0:1], v[0:1], v[28:29]
	v_mov_b32_e32 v160, v22
	v_add_f32_e32 v17, v0, v1
	v_pk_mul_f32 v[0:1], v[70:71], v[12:13] op_sel_hi:[0,1]
	v_mov_b32_e32 v166, v26
	v_mov_b32_e32 v167, v30
	v_sub_f32_e32 v16, v3, v2
	v_pk_mul_f32 v[0:1], v[0:1], v[160:161]
	v_mov_b32_e32 v2, v30
	v_mov_b32_e32 v3, v26
	v_pk_mul_f32 v[2:3], v[0:1], v[2:3]
	v_pk_mul_f32 v[0:1], v[0:1], v[166:167]
	v_mov_b32_e32 v18, v23
	v_add_f32_e32 v13, v0, v1
	v_pk_mul_f32 v[0:1], v[70:71], v[58:59] op_sel_hi:[0,1]
	v_pk_mul_f32 v[0:1], v[0:1], v[18:19]
	v_mov_b32_e32 v26, v31
	v_mov_b32_e32 v30, v27
	v_sub_f32_e32 v12, v3, v2
	v_pk_mul_f32 v[2:3], v[0:1], v[26:27]
	v_pk_mul_f32 v[0:1], v[0:1], v[30:31]
	v_pk_mul_f32 v[66:67], v[66:67], v[64:65]
	v_pk_mul_f32 v[64:65], v[68:69], v[64:65]
	v_sub_f32_e32 v2, v3, v2
	v_add_f32_e32 v0, v0, v1
	v_sub_f32_e32 v20, v67, v66
	v_add_f32_e32 v22, v64, v65
	v_cvt_pk_bf16_f32 v48, v20, v42
	v_cvt_pk_bf16_f32 v49, v6, v44
	v_cvt_pk_bf16_f32 v50, v4, v16
	v_cvt_pk_bf16_f32 v51, v12, v2
	v_cvt_pk_bf16_f32 v116, v22, v43
	v_cvt_pk_bf16_f32 v117, v7, v45
	v_cvt_pk_bf16_f32 v118, v5, v17
	v_cvt_pk_bf16_f32 v119, v13, v0
	ds_read_b128 v[0:3], v243 offset:192
	ds_read_b128 v[4:7], v243 offset:64
	v_or_b32_e32 v96, v96, v127
	v_lshlrev_b32_e32 v12, 2, v96
	ds_read_b128 v[16:19], v252 offset:26240
	ds_read_b128 v[20:23], v252 offset:8192
	ds_read_b128 v[24:27], v243 offset:208
	ds_read_b128 v[28:31], v243 offset:80
	ds_read_b128 v[42:45], v252 offset:30336
	ds_read_b128 v[52:55], v252 offset:12288
	v_pk_mul_f32 v[12:13], v[70:71], v[40:41] op_sel_hi:[0,1]
	v_pk_mul_f32 v[8:9], v[70:71], v[8:9] op_sel_hi:[0,1]
	s_lshl_b32 s69, s97, 6
	s_cmp_eq_u32 s88, 0
	s_cselect_b64 s[78:79], -1, 0
	s_cmp_lg_u32 s88, 0
	s_waitcnt lgkmcnt(0)
	v_mov_b32_e32 v40, v0
	v_mov_b32_e32 v41, v4
	v_pk_mul_f32 v[12:13], v[12:13], v[40:41]
	v_mov_b32_e32 v40, v16
	v_mov_b32_e32 v41, v20
	v_pk_mul_f32 v[40:41], v[12:13], v[40:41]
	v_mov_b32_e32 v4, v1
	v_sub_f32_e32 v46, v41, v40
	v_mov_b32_e32 v40, v20
	v_mov_b32_e32 v41, v16
	v_pk_mul_f32 v[0:1], v[8:9], v[4:5]
	v_mov_b32_e32 v20, v17
	v_mov_b32_e32 v16, v21
	v_pk_mul_f32 v[4:5], v[0:1], v[20:21]
	v_pk_mul_f32 v[0:1], v[0:1], v[16:17]
	v_sub_f32_e32 v8, v5, v4
	v_add_f32_e32 v9, v0, v1
	v_pk_mul_f32 v[0:1], v[70:71], v[38:39] op_sel_hi:[0,1]
	v_mov_b32_e32 v4, v2
	v_mov_b32_e32 v5, v6
	v_pk_mul_f32 v[0:1], v[0:1], v[4:5]
	v_mov_b32_e32 v4, v18
	v_mov_b32_e32 v5, v22
	v_pk_mul_f32 v[12:13], v[12:13], v[40:41]
	v_pk_mul_f32 v[4:5], v[0:1], v[4:5]
	v_add_f32_e32 v12, v12, v13
	v_sub_f32_e32 v13, v5, v4
	v_mov_b32_e32 v4, v22
	v_mov_b32_e32 v5, v18
	v_pk_mul_f32 v[0:1], v[0:1], v[4:5]
	v_mov_b32_e32 v6, v3
	v_add_f32_e32 v4, v0, v1
	v_pk_mul_f32 v[0:1], v[70:71], v[14:15] op_sel_hi:[0,1]
	v_pk_mul_f32 v[0:1], v[0:1], v[6:7]
	v_mov_b32_e32 v22, v19
	v_mov_b32_e32 v18, v23
	v_pk_mul_f32 v[2:3], v[0:1], v[22:23]
	v_pk_mul_f32 v[0:1], v[0:1], v[18:19]
	v_sub_f32_e32 v5, v3, v2
	v_add_f32_e32 v6, v0, v1
	v_pk_mul_f32 v[0:1], v[70:71], v[36:37] op_sel_hi:[0,1]
	v_mov_b32_e32 v2, v24
	v_mov_b32_e32 v3, v28
	v_pk_mul_f32 v[0:1], v[0:1], v[2:3]
	v_mov_b32_e32 v2, v42
	v_mov_b32_e32 v3, v52
	v_pk_mul_f32 v[2:3], v[0:1], v[2:3]
	v_mov_b32_e32 v28, v25
	v_sub_f32_e32 v7, v3, v2
	v_mov_b32_e32 v2, v52
	v_mov_b32_e32 v3, v42
	v_pk_mul_f32 v[0:1], v[0:1], v[2:3]
	v_mov_b32_e32 v52, v43
	v_add_f32_e32 v14, v0, v1
	v_pk_mul_f32 v[0:1], v[70:71], v[10:11] op_sel_hi:[0,1]
	v_pk_mul_f32 v[0:1], v[0:1], v[28:29]
	v_mov_b32_e32 v42, v53
	v_pk_mul_f32 v[2:3], v[0:1], v[52:53]
	v_pk_mul_f32 v[0:1], v[0:1], v[42:43]
	v_sub_f32_e32 v10, v3, v2
	v_add_f32_e32 v11, v0, v1
	v_pk_mul_f32 v[0:1], v[70:71], v[34:35] op_sel_hi:[0,1]
	v_mov_b32_e32 v2, v26
	v_mov_b32_e32 v3, v30
	v_pk_mul_f32 v[0:1], v[0:1], v[2:3]
	v_mov_b32_e32 v2, v44
	v_mov_b32_e32 v3, v54
	v_pk_mul_f32 v[2:3], v[0:1], v[2:3]
	v_mov_b32_e32 v30, v27
	v_sub_f32_e32 v15, v3, v2
	v_mov_b32_e32 v2, v54
	v_mov_b32_e32 v3, v44
	v_pk_mul_f32 v[0:1], v[0:1], v[2:3]
	v_mov_b32_e32 v54, v45
	v_add_f32_e32 v16, v0, v1
	v_pk_mul_f32 v[0:1], v[70:71], v[32:33] op_sel_hi:[0,1]
	v_pk_mul_f32 v[0:1], v[0:1], v[30:31]
	v_mov_b32_e32 v44, v55
	v_pk_mul_f32 v[2:3], v[0:1], v[54:55]
	v_pk_mul_f32 v[0:1], v[0:1], v[44:45]
	v_sub_f32_e32 v2, v3, v2
	v_add_f32_e32 v0, v0, v1
	v_cvt_pk_bf16_f32 v154, v46, v8
	v_cvt_pk_bf16_f32 v155, v13, v5
	v_cvt_pk_bf16_f32 v156, v7, v10
	v_cvt_pk_bf16_f32 v157, v15, v2
	v_cvt_pk_bf16_f32 v158, v12, v9
	v_cvt_pk_bf16_f32 v159, v4, v6
	v_cvt_pk_bf16_f32 v160, v14, v11
	v_cvt_pk_bf16_f32 v161, v16, v0
	s_barrier
	ds_read_b128 v[0:3], v192
	ds_read_b128 v[52:55], v195 offset:32
	s_waitcnt lgkmcnt(1)
	v_mfma_f32_32x32x16_bf16 v[64:79], v[0:3], v[48:51], 0
	ds_read_b128 v[0:3], v192 offset:32
	ds_read_b128 v[162:165], v196 offset:32
	s_waitcnt lgkmcnt(1)
	v_mfma_f32_32x32x16_bf16 v[64:79], v[0:3], v[154:157], v[64:79]
	ds_read_b128 v[0:3], v192 offset:64
	s_waitcnt lgkmcnt(0)
	v_mfma_f32_32x32x16_bf16 v[64:79], v[0:3], v[116:119], v[64:79]
	ds_read_b128 v[0:3], v192 offset:96
	s_waitcnt lgkmcnt(0)
	v_mfma_f32_32x32x16_bf16 v[64:79], v[0:3], v[158:161], v[64:79]
	ds_read_b128 v[0:3], v193
	s_waitcnt lgkmcnt(0)
	v_mfma_f32_32x32x16_bf16 v[32:47], v[0:3], v[48:51], 0
	ds_read_b128 v[0:3], v193 offset:32
	s_waitcnt lgkmcnt(0)
	v_mfma_f32_32x32x16_bf16 v[32:47], v[0:3], v[154:157], v[32:47]
	ds_read_b128 v[0:3], v193 offset:64
	s_waitcnt lgkmcnt(0)
	v_mfma_f32_32x32x16_bf16 v[32:47], v[0:3], v[116:119], v[32:47]
	ds_read_b128 v[0:3], v193 offset:96
	s_waitcnt lgkmcnt(0)
	v_mfma_f32_32x32x16_bf16 v[32:47], v[0:3], v[158:161], v[32:47]
	ds_read_b128 v[0:3], v194
	s_waitcnt lgkmcnt(0)
	v_mfma_f32_32x32x16_bf16 v[16:31], v[0:3], v[48:51], 0
	ds_read_b128 v[0:3], v194 offset:32
	s_waitcnt lgkmcnt(0)
	v_mfma_f32_32x32x16_bf16 v[16:31], v[0:3], v[154:157], v[16:31]
	ds_read_b128 v[0:3], v194 offset:64
	s_waitcnt lgkmcnt(0)
	v_mfma_f32_32x32x16_bf16 v[16:31], v[0:3], v[116:119], v[16:31]
	ds_read_b128 v[0:3], v194 offset:96
	s_waitcnt lgkmcnt(0)
	v_mfma_f32_32x32x16_bf16 v[16:31], v[0:3], v[158:161], v[16:31]
	ds_read_b128 v[0:3], v195
	s_waitcnt lgkmcnt(0)
	v_mfma_f32_32x32x16_bf16 v[0:15], v[0:3], v[48:51], 0
	v_mfma_f32_32x32x16_bf16 v[0:15], v[52:55], v[154:157], v[0:15]
	ds_read_b128 v[52:55], v195 offset:64
	s_waitcnt lgkmcnt(0)
	v_mfma_f32_32x32x16_bf16 v[0:15], v[52:55], v[116:119], v[0:15]
	ds_read_b128 v[52:55], v195 offset:96
	s_waitcnt lgkmcnt(0)
	v_mfma_f32_32x32x16_bf16 v[0:15], v[52:55], v[158:161], v[0:15]
	ds_read_b128 v[52:55], v196
	s_waitcnt lgkmcnt(0)
	v_mfma_f32_32x32x16_bf16 v[48:63], v[52:55], v[48:51], 0
	v_mfma_f32_32x32x16_bf16 v[48:63], v[162:165], v[154:157], v[48:63]
	ds_read_b128 v[154:157], v196 offset:64
	s_waitcnt lgkmcnt(0)
	v_mfma_f32_32x32x16_bf16 v[48:63], v[154:157], v[116:119], v[48:63]
	ds_read_b128 v[116:119], v196 offset:96
	s_waitcnt lgkmcnt(0)
	v_mfma_f32_32x32x16_bf16 v[48:63], v[116:119], v[158:161], v[48:63]
	s_cbranch_scc0 .LBB0_356
	v_cndmask_b32_e64 v158, v212, v64, s[2:3]
	v_cndmask_b32_e64 v157, v65, v212, s[4:5]
	v_cndmask_b32_e64 v156, v212, v66, s[6:7]
	v_cndmask_b32_e64 v155, v212, v67, s[8:9]
	v_cndmask_b32_e64 v154, v212, v68, s[10:11]
	v_cndmask_b32_e64 v119, v212, v69, s[12:13]
	v_cndmask_b32_e64 v118, v212, v70, s[14:15]
	v_cndmask_b32_e64 v99, v212, v71, s[16:17]
	v_cndmask_b32_e64 v71, v212, v72, s[18:19]
	v_cndmask_b32_e64 v70, v212, v73, s[20:21]
	v_cndmask_b32_e64 v69, v212, v74, s[22:23]
	v_cndmask_b32_e64 v68, v212, v75, s[24:25]
	v_cndmask_b32_e64 v67, v212, v76, s[26:27]
	v_cndmask_b32_e64 v66, v212, v77, s[28:29]
	v_cndmask_b32_e64 v65, v212, v78, s[30:31]
	v_cndmask_b32_e64 v64, v212, v79, s[34:35]
	s_branch .LBB0_357

.Lvpf_skip:
	ds_read_b128 v[0:3], v243 offset:16
	s_nop 0
	ds_read_b128 v[16:19], v243
	ds_read_b128 v[4:7], v243 offset:144
	ds_read_b128 v[20:23], v243 offset:128
	v_lshlrev_b32_e32 v28, 5, v118
	v_or_b32_e32 v8, v28, v126
	v_lshlrev_b32_e32 v29, 2, v8
	ds_read_b128 v[8:11], v252 offset:6144
	ds_read_b128 v[24:27], v252 offset:2048
	ds_read_b128 v[12:15], v252 offset:24192
	ds_read_b128 v[44:47], v252 offset:20096
	v_or_b32_e32 v28, v28, v127
	v_lshlrev_b32_e32 v119, 2, v28
	v_lshlrev_b32_e32 v30, 16, v115
	v_and_b32_e32 v28, 0xffff0000, v115
	v_mov_b32_e32 v32, v28
	v_mov_b32_e32 v33, v30
	v_pk_mul_f32 v[48:49], v[32:33], v[32:33]
	v_lshlrev_b32_e32 v34, 16, v114
	v_and_b32_e32 v32, 0xffff0000, v114
	v_mov_b32_e32 v36, v32
	v_mov_b32_e32 v37, v34
	v_pk_mul_f32 v[50:51], v[36:37], v[36:37]
	v_and_b32_e32 v36, 0xffff0000, v113
	v_mov_b32_e32 v40, v36
	v_and_b32_e32 v113, 0xffff0000, v101
	v_and_b32_e32 v101, 0xffff0000, v100
	v_and_b32_e32 v100, 0xffff0000, v104
	v_pk_mul_f32 v[52:53], v[40:41], v[40:41]
	v_and_b32_e32 v40, 0xffff0000, v112
	v_and_b32_e32 v112, 0xffff0000, v105
	v_pk_mul_f32 v[104:105], v[100:101], v[100:101]
	v_pk_mul_f32 v[114:115], v[112:113], v[112:113]
	v_and_b32_e32 v41, 0xffff0000, v108
	v_pk_mul_f32 v[56:57], v[40:41], v[40:41]
	v_and_b32_e32 v37, 0xffff0000, v109
	v_lshlrev_b32_e32 v35, 16, v110
	v_and_b32_e32 v33, 0xffff0000, v110
	v_lshlrev_b32_e32 v31, 16, v111
	v_and_b32_e32 v29, 0xffff0000, v111
	s_andn2_b64 vcc, exec, s[78:79]
	s_waitcnt lgkmcnt(0)
	v_mov_b32_e32 v75, v0
	v_add_f32_e32 v0, v157, v105
	v_add_f32_e32 v0, v107, v0
	v_add_f32_e32 v0, v115, v0
	v_add_f32_e32 v0, v73, v0
	v_add_f32_e32 v0, v99, v0
	v_add_f32_e32 v0, v61, v0
	v_add_f32_e32 v0, v69, v0
	v_add_f32_e32 v0, v55, v0
	v_add_f32_e32 v0, v57, v0
	v_fmac_f32_e32 v0, v39, v39
	v_fmac_f32_e32 v0, v37, v37
	v_fmac_f32_e32 v0, v35, v35
	v_fmac_f32_e32 v0, v33, v33
	v_fmac_f32_e32 v0, v31, v31
	v_fmac_f32_e32 v0, v29, v29
	v_add_f32_e32 v0, v156, v0
	v_add_f32_e32 v0, v104, v0
	v_add_f32_e32 v0, v106, v0
	v_add_f32_e32 v0, v114, v0
	v_add_f32_e32 v0, v72, v0
	v_add_f32_e32 v0, v98, v0
	v_add_f32_e32 v0, v60, v0
	v_add_f32_e32 v0, v68, v0
	v_add_f32_e32 v0, v54, v0
	v_add_f32_e32 v0, v56, v0
	v_add_f32_e32 v0, v53, v0
	v_add_f32_e32 v0, v52, v0
	v_add_f32_e32 v0, v51, v0
	v_add_f32_e32 v0, v50, v0
	v_add_f32_e32 v0, v49, v0
	v_add_f32_e32 v0, v48, v0
	v_mov_b32_e32 v63, v2
	v_mov_b32_e32 v142, v0
	v_mov_b32_e32 v143, v0
	s_nop 1
	v_permlane32_swap_b32_e32 v142, v143
	v_mov_b32_e32 v74, v4
	v_mov_b32_e32 v158, v20
	v_mov_b32_e32 v159, v16
	v_mov_b32_e32 v160, v24
	v_add_f32_e32 v0, v142, v143
	v_fmamk_f32 v0, v0, 0x3c800000, v189
	v_rsq_f32_e32 v0, v0
	v_mov_b32_e32 v161, v44
	v_mov_b32_e32 v50, v44
	v_mov_b32_e32 v51, v24
	v_mul_f32_e32 v4, 0x3e38aa3b, v0
	v_pk_mul_f32 v[48:49], v[4:5], v[154:155] op_sel_hi:[0,1]
	v_pk_mul_f32 v[48:49], v[158:159], v[48:49]
	v_mov_b32_e32 v108, v22
	v_pk_mul_f32 v[50:51], v[50:51], v[48:49]
	v_pk_mul_f32 v[48:49], v[160:161], v[48:49]
	v_mov_b32_e32 v16, v21
	v_add_f32_e32 v22, v48, v49
	v_pk_mul_f32 v[48:49], v[4:5], v[100:101] op_sel_hi:[0,1]
	v_pk_mul_f32 v[16:17], v[16:17], v[48:49]
	v_mov_b32_e32 v24, v45
	v_mov_b32_e32 v44, v25
	v_pk_mul_f32 v[20:21], v[24:25], v[16:17]
	v_pk_mul_f32 v[16:17], v[44:45], v[16:17]
	v_mov_b32_e32 v109, v18
	v_add_f32_e32 v25, v16, v17
	v_pk_mul_f32 v[16:17], v[4:5], v[102:103] op_sel_hi:[0,1]
	v_mov_b32_e32 v110, v26
	v_mov_b32_e32 v111, v46
	v_sub_f32_e32 v24, v21, v20
	v_pk_mul_f32 v[16:17], v[16:17], v[108:109]
	v_mov_b32_e32 v20, v46
	v_mov_b32_e32 v21, v26
	v_pk_mul_f32 v[20:21], v[16:17], v[20:21]
	v_pk_mul_f32 v[16:17], v[16:17], v[110:111]
	v_sub_f32_e32 v20, v21, v20
	v_add_f32_e32 v21, v16, v17
	v_pk_mul_f32 v[16:17], v[4:5], v[112:113] op_sel_hi:[0,1]
	v_mov_b32_e32 v18, v23
	v_pk_mul_f32 v[16:17], v[16:17], v[18:19]
	v_mov_b32_e32 v26, v47
	v_mov_b32_e32 v46, v27
	v_pk_mul_f32 v[18:19], v[16:17], v[26:27]
	v_pk_mul_f32 v[16:17], v[16:17], v[46:47]
	v_mov_b32_e32 v76, v8
	v_add_f32_e32 v26, v16, v17
	v_pk_mul_f32 v[16:17], v[4:5], v[70:71] op_sel_hi:[0,1]
	v_mov_b32_e32 v77, v12
	v_sub_f32_e32 v23, v19, v18
	v_pk_mul_f32 v[16:17], v[16:17], v[74:75]
	v_mov_b32_e32 v18, v12
	v_mov_b32_e32 v19, v8
	v_pk_mul_f32 v[18:19], v[16:17], v[18:19]
	v_pk_mul_f32 v[16:17], v[16:17], v[76:77]
	v_sub_f32_e32 v18, v19, v18
	v_add_f32_e32 v19, v16, v17
	v_pk_mul_f32 v[16:17], v[4:5], v[78:79] op_sel_hi:[0,1]
	v_mov_b32_e32 v0, v5
	v_pk_mul_f32 v[0:1], v[16:17], v[0:1]
	v_mov_b32_e32 v8, v13
	v_pk_mul_f32 v[16:17], v[0:1], v[8:9]
	v_mov_b32_e32 v12, v9
	v_sub_f32_e32 v5, v17, v16
	v_pk_mul_f32 v[0:1], v[0:1], v[12:13]
	v_mov_b32_e32 v62, v6
	v_add_f32_e32 v12, v0, v1
	v_pk_mul_f32 v[0:1], v[4:5], v[58:59] op_sel_hi:[0,1]
	v_mov_b32_e32 v64, v10
	v_mov_b32_e32 v65, v14
	v_pk_mul_f32 v[0:1], v[0:1], v[62:63]
	v_mov_b32_e32 v8, v14
	v_mov_b32_e32 v9, v10
	v_pk_mul_f32 v[8:9], v[0:1], v[8:9]
	v_pk_mul_f32 v[0:1], v[0:1], v[64:65]
	v_sub_f32_e32 v8, v9, v8
	v_add_f32_e32 v9, v0, v1
	v_pk_mul_f32 v[0:1], v[4:5], v[66:67] op_sel_hi:[0,1]
	v_mov_b32_e32 v2, v7
	v_pk_mul_f32 v[0:1], v[0:1], v[2:3]
	v_mov_b32_e32 v10, v15
	v_mov_b32_e32 v14, v11
	v_pk_mul_f32 v[2:3], v[0:1], v[10:11]
	v_pk_mul_f32 v[0:1], v[0:1], v[14:15]
	v_sub_f32_e32 v6, v51, v50
	v_sub_f32_e32 v2, v3, v2
	v_add_f32_e32 v0, v0, v1
	v_cvt_pk_bf16_f32 v48, v6, v24
	v_cvt_pk_bf16_f32 v49, v20, v23
	v_cvt_pk_bf16_f32 v50, v18, v5
	v_cvt_pk_bf16_f32 v51, v8, v2
	v_cvt_pk_bf16_f32 v98, v22, v25
	v_cvt_pk_bf16_f32 v99, v21, v26
	v_cvt_pk_bf16_f32 v100, v19, v12
	v_cvt_pk_bf16_f32 v101, v9, v0
	ds_read_b128 v[0:3], v243 offset:80
	ds_read_b128 v[6:9], v243 offset:64
	ds_read_b128 v[10:13], v243 offset:208
	ds_read_b128 v[14:17], v243 offset:192
	v_pk_mul_f32 v[18:19], v[4:5], v[42:43] op_sel_hi:[0,1]
	s_waitcnt lgkmcnt(0)
	v_mov_b32_e32 v21, v6
	v_mov_b32_e32 v20, v14
	v_pk_mul_f32 v[26:27], v[18:19], v[20:21]
	ds_read_b128 v[18:21], v252 offset:14336
	ds_read_b128 v[22:25], v252 offset:10240
	ds_read_b128 v[42:45], v252 offset:32384
	ds_read_b128 v[52:55], v252 offset:28288
	v_mov_b32_e32 v6, v15
	s_waitcnt lgkmcnt(0)
	v_mov_b32_e32 v47, v22
	v_mov_b32_e32 v46, v52
	v_pk_mul_f32 v[46:47], v[26:27], v[46:47]
	s_nop 0
	v_sub_f32_e32 v5, v47, v46
	v_mov_b32_e32 v46, v22
	v_mov_b32_e32 v47, v52
	v_pk_mul_f32 v[26:27], v[26:27], v[46:47]
	v_mov_b32_e32 v22, v53
	v_add_f32_e32 v46, v26, v27
	v_pk_mul_f32 v[26:27], v[4:5], v[40:41] op_sel_hi:[0,1]
	v_pk_mul_f32 v[6:7], v[26:27], v[6:7]
	v_mov_b32_e32 v52, v23
	v_pk_mul_f32 v[14:15], v[6:7], v[22:23]
	v_pk_mul_f32 v[6:7], v[6:7], v[52:53]
	v_sub_f32_e32 v22, v15, v14
	v_add_f32_e32 v23, v6, v7
	v_pk_mul_f32 v[6:7], v[4:5], v[38:39] op_sel_hi:[0,1]
	v_mov_b32_e32 v14, v16
	v_mov_b32_e32 v15, v8
	v_pk_mul_f32 v[6:7], v[6:7], v[14:15]
	v_mov_b32_e32 v14, v54
	v_mov_b32_e32 v15, v24
	v_pk_mul_f32 v[14:15], v[6:7], v[14:15]
	v_mov_b32_e32 v8, v17
	v_sub_f32_e32 v16, v15, v14
	v_mov_b32_e32 v14, v24
	v_mov_b32_e32 v15, v54
	v_pk_mul_f32 v[6:7], v[6:7], v[14:15]
	v_mov_b32_e32 v24, v55
	v_add_f32_e32 v14, v6, v7
	v_pk_mul_f32 v[6:7], v[4:5], v[36:37] op_sel_hi:[0,1]
	v_pk_mul_f32 v[6:7], v[6:7], v[8:9]
	v_mov_b32_e32 v54, v25
	v_pk_mul_f32 v[8:9], v[6:7], v[24:25]
	v_pk_mul_f32 v[6:7], v[6:7], v[54:55]
	v_sub_f32_e32 v15, v9, v8
	v_add_f32_e32 v17, v6, v7
	v_pk_mul_f32 v[6:7], v[4:5], v[34:35] op_sel_hi:[0,1]
	v_mov_b32_e32 v8, v10
	v_mov_b32_e32 v9, v0
	v_pk_mul_f32 v[6:7], v[6:7], v[8:9]
	v_mov_b32_e32 v8, v42
	v_mov_b32_e32 v9, v18
	v_pk_mul_f32 v[8:9], v[6:7], v[8:9]
	v_mov_b32_e32 v0, v11
	v_sub_f32_e32 v10, v9, v8
	v_mov_b32_e32 v8, v18
	v_mov_b32_e32 v9, v42
	v_pk_mul_f32 v[6:7], v[6:7], v[8:9]
	v_mov_b32_e32 v18, v43
	v_add_f32_e32 v8, v6, v7
	v_pk_mul_f32 v[6:7], v[4:5], v[32:33] op_sel_hi:[0,1]
	v_pk_mul_f32 v[0:1], v[6:7], v[0:1]
	v_mov_b32_e32 v42, v19
	v_pk_mul_f32 v[6:7], v[0:1], v[18:19]
	v_pk_mul_f32 v[0:1], v[0:1], v[42:43]
	v_sub_f32_e32 v9, v7, v6
	v_add_f32_e32 v11, v0, v1
	v_pk_mul_f32 v[0:1], v[4:5], v[30:31] op_sel_hi:[0,1]
	v_mov_b32_e32 v6, v12
	v_mov_b32_e32 v7, v2
	v_pk_mul_f32 v[0:1], v[0:1], v[6:7]
	v_mov_b32_e32 v6, v44
	v_mov_b32_e32 v7, v20
	v_pk_mul_f32 v[6:7], v[0:1], v[6:7]
	v_mov_b32_e32 v2, v13
	v_sub_f32_e32 v12, v7, v6
	v_mov_b32_e32 v6, v20
	v_mov_b32_e32 v7, v44
	v_pk_mul_f32 v[0:1], v[0:1], v[6:7]
	v_mov_b32_e32 v20, v45
	v_add_f32_e32 v6, v0, v1
	v_pk_mul_f32 v[0:1], v[4:5], v[28:29] op_sel_hi:[0,1]
	v_pk_mul_f32 v[0:1], v[0:1], v[2:3]
	v_mov_b32_e32 v44, v21
	v_pk_mul_f32 v[2:3], v[0:1], v[20:21]
	v_pk_mul_f32 v[0:1], v[0:1], v[44:45]
	v_sub_f32_e32 v2, v3, v2
	v_add_f32_e32 v0, v0, v1
	v_cvt_pk_bf16_f32 v102, v5, v22
	v_cvt_pk_bf16_f32 v103, v16, v15
	v_cvt_pk_bf16_f32 v104, v10, v9
	v_cvt_pk_bf16_f32 v105, v12, v2
	v_cvt_pk_bf16_f32 v106, v46, v23
	v_cvt_pk_bf16_f32 v107, v14, v17
	v_cvt_pk_bf16_f32 v108, v8, v11
	v_cvt_pk_bf16_f32 v109, v6, v0
	ds_read_b128 v[0:3], v202
	ds_read_b128 v[4:7], v202 offset:32
	s_waitcnt lgkmcnt(1)
	v_mfma_f32_32x32x16_bf16 v[64:79], v[0:3], v[48:51], 0
	ds_read_b128 v[0:3], v202 offset:64
	s_waitcnt lgkmcnt(1)
	v_mfma_f32_32x32x16_bf16 v[64:79], v[4:7], v[102:105], v[64:79]
	s_waitcnt lgkmcnt(0)
	v_mfma_f32_32x32x16_bf16 v[64:79], v[0:3], v[98:101], v[64:79]
	ds_read_b128 v[0:3], v202 offset:96
	s_waitcnt lgkmcnt(0)
	v_mfma_f32_32x32x16_bf16 v[64:79], v[0:3], v[106:109], v[64:79]
	ds_read_b128 v[0:3], v203
	ds_read_b128 v[4:7], v203 offset:32
	s_waitcnt lgkmcnt(1)
	v_mfma_f32_32x32x16_bf16 v[32:47], v[0:3], v[48:51], 0
	ds_read_b128 v[0:3], v203 offset:64
	s_waitcnt lgkmcnt(1)
	v_mfma_f32_32x32x16_bf16 v[32:47], v[4:7], v[102:105], v[32:47]
	s_waitcnt lgkmcnt(0)
	v_mfma_f32_32x32x16_bf16 v[32:47], v[0:3], v[98:101], v[32:47]
	ds_read_b128 v[0:3], v203 offset:96
	s_waitcnt lgkmcnt(0)
	v_mfma_f32_32x32x16_bf16 v[32:47], v[0:3], v[106:109], v[32:47]
	ds_read_b128 v[0:3], v204
	ds_read_b128 v[4:7], v204 offset:32
	s_waitcnt lgkmcnt(1)
	v_mfma_f32_32x32x16_bf16 v[16:31], v[0:3], v[48:51], 0
	ds_read_b128 v[0:3], v204 offset:64
	s_waitcnt lgkmcnt(1)
	v_mfma_f32_32x32x16_bf16 v[16:31], v[4:7], v[102:105], v[16:31]
	s_waitcnt lgkmcnt(0)
	v_mfma_f32_32x32x16_bf16 v[16:31], v[0:3], v[98:101], v[16:31]
	ds_read_b128 v[0:3], v204 offset:96
	s_waitcnt lgkmcnt(0)
	v_mfma_f32_32x32x16_bf16 v[16:31], v[0:3], v[106:109], v[16:31]
	ds_read_b128 v[0:3], v205
	ds_read_b128 v[52:55], v205 offset:32
	s_waitcnt lgkmcnt(1)
	v_mfma_f32_32x32x16_bf16 v[0:15], v[0:3], v[48:51], 0
	s_waitcnt lgkmcnt(0)
	v_mfma_f32_32x32x16_bf16 v[0:15], v[52:55], v[102:105], v[0:15]
	ds_read_b128 v[52:55], v205 offset:64
	s_waitcnt lgkmcnt(0)
	v_mfma_f32_32x32x16_bf16 v[0:15], v[52:55], v[98:101], v[0:15]
	ds_read_b128 v[52:55], v205 offset:96
	s_waitcnt lgkmcnt(0)
	v_mfma_f32_32x32x16_bf16 v[0:15], v[52:55], v[106:109], v[0:15]
	ds_read_b128 v[52:55], v206
	ds_read_b128 v[110:113], v206 offset:32
	s_waitcnt lgkmcnt(1)
	v_mfma_f32_32x32x16_bf16 v[48:63], v[52:55], v[48:51], 0
	s_waitcnt lgkmcnt(0)
	v_mfma_f32_32x32x16_bf16 v[48:63], v[110:113], v[102:105], v[48:63]
	ds_read_b128 v[102:105], v206 offset:64
	s_waitcnt lgkmcnt(0)
	v_mfma_f32_32x32x16_bf16 v[48:63], v[102:105], v[98:101], v[48:63]
	ds_read_b128 v[98:101], v206 offset:96
	s_waitcnt lgkmcnt(0)
	v_mfma_f32_32x32x16_bf16 v[48:63], v[98:101], v[106:109], v[48:63]
	s_cbranch_vccz .LBB0_346
	v_cndmask_b32_e64 v98, v212, v64, s[2:3]
	v_cndmask_b32_e64 v105, v65, v212, s[4:5]
	v_cndmask_b32_e64 v104, v212, v66, s[6:7]
	v_cndmask_b32_e64 v103, v212, v67, s[8:9]
	v_cndmask_b32_e64 v102, v212, v68, s[10:11]
	v_cndmask_b32_e64 v101, v212, v69, s[12:13]
	v_cndmask_b32_e64 v100, v212, v70, s[14:15]
	v_cndmask_b32_e64 v99, v212, v71, s[16:17]
	v_cndmask_b32_e64 v71, v212, v72, s[18:19]
	v_cndmask_b32_e64 v70, v212, v73, s[20:21]
	v_cndmask_b32_e64 v69, v212, v74, s[22:23]
	v_cndmask_b32_e64 v68, v212, v75, s[24:25]
	v_cndmask_b32_e64 v67, v212, v76, s[26:27]
	v_cndmask_b32_e64 v66, v212, v77, s[28:29]
	v_cndmask_b32_e64 v65, v212, v78, s[30:31]
	v_cndmask_b32_e64 v64, v212, v79, s[34:35]
	s_branch .LBB0_347
